# combo23 + dn_prep step-2 first six z-row loads issued before the wave-0-only step 1
# speedup vs baseline: 1.0031x; 1.0031x over previous
; __device__ __forceinline__ void dn_prep(const Params& p, LAS unsigned char* lds) {
;     ...
;             const int t = tid2 >> 3, sub = tid2 & 7, d0 = sub * 16;
;             const bool valid = t < ntok;
;             const bool whist = valid && (samp || n == 31) && (t >= ntok - 3);
;             float* hist_out = p.out + (samp ? O_SBC : O_PBC) + (size_t)(b * 3 + (t - (ntok - 3))) * 1536;
; #pragma unroll
;             for (int part = 0; part < 3; ++part) {
;                 bf16x8 raw[4][2];
; #pragma unroll
;                 for (int j = 0; j < 4; ++j) { const int tt = t - 3 + j; int te = (tt >= 0 || (!samp && n > 0)) ? tt : 0; te = te < ntok ? te : ntok - 1;
;                     const bf16_t* zp = Z + (size_t)(row0 + te) * NZ + ZC_BQKV + part * 512 + h * 128 + d0;
;                     raw[j][0] = *(const bf16x8*)zp; raw[j][1] = *(const bf16x8*)(zp + 8); }
.LBB0_197:
	s_ashr_i32 s89, s88, 31
	s_cmp_eq_u32 s16, 0
	s_cselect_b64 s[94:95], -1, 0
	s_or_b64 s[94:95], s[68:69], s[94:95]
	s_add_i32 s96, s6, -1
	s_lshl_b32 s98, s17, 8
	s_mov_b32 s99, 0
	v_ashrrev_i32_e32 v176, 3, v184
	v_and_b32_e32 v177, 7, v184
	v_lshlrev_b32_e32 v182, 5, v177
	v_mov_b32_e32 v183, 0
	v_add_u32_e32 v178, -2, v176
	v_max_i32_e32 v179, 0, v178
	v_cndmask_b32_e64 v178, v178, v179, s[94:95]
	v_min_i32_e32 v178, s96, v178
	v_add_u32_e32 v178, s90, v178
	v_mov_b64_e32 v[180:181], s[50:51]
	s_nop 0
	v_mad_i64_i32 v[180:181], s[92:93], v178, s38, v[180:181]
	v_lshl_add_u64 v[180:181], v[180:181], 0, s[98:99]
	v_lshl_add_u64 v[180:181], v[180:181], 0, v[182:183]
	v_lshl_add_u64 v[180:181], v[180:181], 0, s[42:43]
	global_load_dwordx4 v[60:63], v[180:181], off
	global_load_dwordx4 v[56:59], v[180:181], off offset:16
	v_add_u32_e32 v178, -1, v176
	v_max_i32_e32 v179, 0, v178
	v_cndmask_b32_e64 v178, v178, v179, s[94:95]
	v_min_i32_e32 v178, s96, v178
	v_add_u32_e32 v178, s90, v178
	v_mov_b64_e32 v[180:181], s[50:51]
	s_nop 0
	v_mad_i64_i32 v[180:181], s[92:93], v178, s38, v[180:181]
	v_lshl_add_u64 v[180:181], v[180:181], 0, s[98:99]
	v_lshl_add_u64 v[180:181], v[180:181], 0, v[182:183]
	v_lshl_add_u64 v[180:181], v[180:181], 0, s[42:43]
	global_load_dwordx4 v[92:95], v[180:181], off
	global_load_dwordx4 v[88:91], v[180:181], off offset:16
	v_add_u32_e32 v178, 0, v176
	v_max_i32_e32 v179, 0, v178
	v_cndmask_b32_e64 v178, v178, v179, s[94:95]
	v_min_i32_e32 v178, s96, v178
	v_add_u32_e32 v178, s90, v178
	v_mov_b64_e32 v[180:181], s[50:51]
	s_nop 0
	v_mad_i64_i32 v[180:181], s[92:93], v178, s38, v[180:181]
	v_lshl_add_u64 v[180:181], v[180:181], 0, s[98:99]
	v_lshl_add_u64 v[180:181], v[180:181], 0, v[182:183]
	v_lshl_add_u64 v[180:181], v[180:181], 0, s[42:43]
	global_load_dwordx4 v[52:55], v[180:181], off
	global_load_dwordx4 v[48:51], v[180:181], off offset:16
	s_and_saveexec_b64 s[24:25], s[2:3]
	s_cbranch_execnz .LBB0_200
	s_branch .LBB0_205

; __device__ __forceinline__ void dn_prep(const Params& p, LAS unsigned char* lds) {
;     ...
;         int b, n, h, chs, row0, ntok;
;         if (!samp) { h = ci & 3; n = (ci >> 2) & 31; b = ci >> 7; chs = ((b * 4 + h) << 5) + n; row0 = b * 2048 + n * 64; ntok = 64; }
;         else { const int s = ci - 1024; h = s & 3; b = s >> 2; n = 0; chs = 1024 + s; row0 = MP + b * 16; ntok = 16; }
;     ...
;             const int t = tid2 >> 3, sub = tid2 & 7, d0 = sub * 16;
;             const bool valid = t < ntok;
;             const bool whist = valid && (samp || n == 31) && (t >= ntok - 3);
;             float* hist_out = p.out + (samp ? O_SBC : O_PBC) + (size_t)(b * 3 + (t - (ntok - 3))) * 1536;
; #pragma unroll
;             for (int part = 0; part < 3; ++part) {
;                 bf16x8 raw[4][2];
; #pragma unroll
;                 for (int j = 0; j < 4; ++j) { const int tt = t - 3 + j; int te = (tt >= 0 || (!samp && n > 0)) ? tt : 0; te = te < ntok ? te : ntok - 1;
;                     const bf16_t* zp = Z + (size_t)(row0 + te) * NZ + ZC_BQKV + part * 512 + h * 128 + d0;
;                     raw[j][0] = *(const bf16x8*)zp; raw[j][1] = *(const bf16x8*)(zp + 8); }
.LBB0_199:
	s_add_i32 s0, s30, 0xfffffc00
	s_lshr_b32 s7, s0, 2
	s_lshl_b32 s0, s7, 4
	s_add_i32 s90, s0, 0x4000
	s_mov_b32 s16, 0
	s_mov_b32 s6, 16
	s_mov_b32 s88, s30
	s_ashr_i32 s89, s88, 31
	s_cmp_eq_u32 s16, 0
	s_cselect_b64 s[94:95], -1, 0
	s_or_b64 s[94:95], s[68:69], s[94:95]
	s_add_i32 s96, s6, -1
	s_lshl_b32 s98, s17, 8
	s_mov_b32 s99, 0
	v_ashrrev_i32_e32 v176, 3, v184
	v_and_b32_e32 v177, 7, v184
	v_lshlrev_b32_e32 v182, 5, v177
	v_mov_b32_e32 v183, 0
	v_add_u32_e32 v178, -2, v176
	v_max_i32_e32 v179, 0, v178
	v_cndmask_b32_e64 v178, v178, v179, s[94:95]
	v_min_i32_e32 v178, s96, v178
	v_add_u32_e32 v178, s90, v178
	v_mov_b64_e32 v[180:181], s[50:51]
	s_nop 0
	v_mad_i64_i32 v[180:181], s[92:93], v178, s38, v[180:181]
	v_lshl_add_u64 v[180:181], v[180:181], 0, s[98:99]
	v_lshl_add_u64 v[180:181], v[180:181], 0, v[182:183]
	v_lshl_add_u64 v[180:181], v[180:181], 0, s[42:43]
	global_load_dwordx4 v[60:63], v[180:181], off
	global_load_dwordx4 v[56:59], v[180:181], off offset:16
	v_add_u32_e32 v178, -1, v176
	v_max_i32_e32 v179, 0, v178
	v_cndmask_b32_e64 v178, v178, v179, s[94:95]
	v_min_i32_e32 v178, s96, v178
	v_add_u32_e32 v178, s90, v178
	v_mov_b64_e32 v[180:181], s[50:51]
	s_nop 0
	v_mad_i64_i32 v[180:181], s[92:93], v178, s38, v[180:181]
	v_lshl_add_u64 v[180:181], v[180:181], 0, s[98:99]
	v_lshl_add_u64 v[180:181], v[180:181], 0, v[182:183]
	v_lshl_add_u64 v[180:181], v[180:181], 0, s[42:43]
	global_load_dwordx4 v[92:95], v[180:181], off
	global_load_dwordx4 v[88:91], v[180:181], off offset:16
	v_add_u32_e32 v178, 0, v176
	v_max_i32_e32 v179, 0, v178
	v_cndmask_b32_e64 v178, v178, v179, s[94:95]
	v_min_i32_e32 v178, s96, v178
	v_add_u32_e32 v178, s90, v178
	v_mov_b64_e32 v[180:181], s[50:51]
	s_nop 0
	v_mad_i64_i32 v[180:181], s[92:93], v178, s38, v[180:181]
	v_lshl_add_u64 v[180:181], v[180:181], 0, s[98:99]
	v_lshl_add_u64 v[180:181], v[180:181], 0, v[182:183]
	v_lshl_add_u64 v[180:181], v[180:181], 0, s[42:43]
	global_load_dwordx4 v[52:55], v[180:181], off
	global_load_dwordx4 v[48:51], v[180:181], off offset:16
	s_and_saveexec_b64 s[24:25], s[2:3]
	s_cbranch_execz .LBB0_205

; __device__ __forceinline__ float bf2f(short b) { return __uint_as_float(((unsigned)(unsigned short)b) << 16); }
; __device__ __forceinline__ void dn_prep(const Params& p, LAS unsigned char* lds) {
;     ...
;             const int t = tid2 >> 3, sub = tid2 & 7, d0 = sub * 16;
;             const bool valid = t < ntok;
;             const bool whist = valid && (samp || n == 31) && (t >= ntok - 3);
;             float* hist_out = p.out + (samp ? O_SBC : O_PBC) + (size_t)(b * 3 + (t - (ntok - 3))) * 1536;
; #pragma unroll
;             for (int part = 0; part < 3; ++part) {
;                 bf16x8 raw[4][2];
; #pragma unroll
;                 for (int j = 0; j < 4; ++j) { const int tt = t - 3 + j; int te = (tt >= 0 || (!samp && n > 0)) ? tt : 0; te = te < ntok ? te : ntok - 1;
;                     const bf16_t* zp = Z + (size_t)(row0 + te) * NZ + ZC_BQKV + part * 512 + h * 128 + d0;
;                     raw[j][0] = *(const bf16x8*)zp; raw[j][1] = *(const bf16x8*)(zp + 8); }
;                 const int c0 = part * 512 + h * 128 + d0;
;                 float y[16];
; #pragma unroll
;                 for (int e = 0; e < 16; ++e) y[e] = 0.f;
; #pragma unroll
;                 for (int j = 0; j < 4; ++j) {
;                     const int tt = t - 3 + j;
;                     float xv[16];
;                     if (valid && (tt >= 0 || (!samp && n > 0))) {
; #pragma unroll
;                         for (int e = 0; e < 8; ++e) { xv[e] = bf2f(raw[j][0][e]); xv[8 + e] = bf2f(raw[j][1][e]); }
;                     } else if (valid && samp) {
;                         const float* hp = p.in[5] + (size_t)(b * 3 + (3 + tt)) * 1536 + c0;
; #pragma unroll
;                         for (int e4 = 0; e4 < 4; ++e4) { const float4 q4 = *(const float4*)(hp + e4 * 4); xv[e4 * 4] = q4.x; xv[e4 * 4 + 1] = q4.y; xv[e4 * 4 + 2] = q4.z; xv[e4 * 4 + 3] = q4.w; }
.LBB0_205:
	s_or_b64 exec, exec, s[24:25]
	v_mov_b32 v0, 0
	s_cmp_eq_u32 s16, 0
	v_add_u32_e32 v235, v0, v184
	v_ashrrev_i32_e32 v232, 3, v235
	s_cselect_b64 s[0:1], -1, 0
	v_add_u32_e32 v2, -2, v232
	s_or_b64 s[26:27], s[68:69], s[0:1]
	v_max_i32_e32 v3, 0, v2
	v_add_u32_e32 v0, -3, v232
	s_add_i32 s18, s6, -1
	v_cndmask_b32_e64 v2, v2, v3, s[26:27]
	v_max_i32_e32 v1, 0, v0
	v_min_i32_e32 v2, s18, v2
	v_cndmask_b32_e64 v6, v0, v1, s[26:27]
	v_mov_b64_e32 v[0:1], s[50:51]
	v_add_u32_e32 v2, s90, v2
	v_and_b32_e32 v139, 7, v235
	v_mad_i64_i32 v[130:131], s[0:1], v2, s38, v[0:1]
	s_lshl_b32 s40, s17, 8
	v_lshl_add_u64 v[2:3], v[130:131], 0, s[40:41]
	v_lshlrev_b32_e32 v132, 5, v139
	v_lshl_add_u64 v[2:3], v[2:3], 0, v[132:133]
	v_lshl_add_u64 v[4:5], v[2:3], 0, s[42:43]
	v_add_co_u32_e32 v2, vcc, s8, v2
	v_lshlrev_b32_e32 v234, 4, v139
	s_nop 0
	v_addc_co_u32_e32 v3, vcc, 0, v3, vcc
	v_add_u32_e32 v2, -1, v232
	v_max_i32_e32 v3, 0, v2
	v_cndmask_b32_e64 v2, v2, v3, s[26:27]
	v_min_i32_e32 v2, s18, v2
	v_add_u32_e32 v2, s90, v2
	v_mad_i64_i32 v[144:145], s[0:1], v2, s38, v[0:1]
	v_lshl_add_u64 v[2:3], v[144:145], 0, s[40:41]
	v_lshl_add_u64 v[2:3], v[2:3], 0, v[132:133]
	v_lshl_add_u64 v[4:5], v[2:3], 0, s[42:43]
	v_add_co_u32_e32 v2, vcc, s8, v2
	v_cmp_le_i32_e64 s[28:29], s6, v232
	s_nop 0
	v_addc_co_u32_e32 v3, vcc, 0, v3, vcc
	v_max_i32_e32 v2, 0, v232
	v_cndmask_b32_e64 v2, v232, v2, s[26:27]
	v_min_i32_e32 v2, s18, v2
	v_add_u32_e32 v2, s90, v2
	v_mad_i64_i32 v[146:147], s[0:1], v2, s38, v[0:1]
	v_lshl_add_u64 v[2:3], v[146:147], 0, s[40:41]
	v_lshl_add_u64 v[2:3], v[2:3], 0, v[132:133]
	v_lshl_add_u64 v[4:5], v[2:3], 0, s[42:43]
	v_add_co_u32_e32 v2, vcc, 0x3000000, v2
	v_cmp_gt_i32_e64 s[24:25], s6, v232
	s_nop 0
	v_addc_co_u32_e32 v3, vcc, 0, v3, vcc
	v_min_i32_e32 v2, s18, v6
	v_add_u32_e32 v2, s90, v2
	v_mad_i64_i32 v[128:129], s[0:1], v2, s38, v[0:1]
	v_cmp_gt_i32_e32 vcc, 3, v232
	s_and_b64 s[0:1], s[26:27], vcc
	s_lshl_b32 s17, s17, 7
	s_nor_b64 s[92:93], s[0:1], s[28:29]
	v_lshlrev_b32_e32 v132, 1, v234
	s_and_saveexec_b64 s[0:1], s[92:93]
	s_xor_b64 s[90:91], exec, s[0:1]
	s_cbranch_execz .LBB0_207
	s_lshl_b32 s40, s17, 1
	v_lshl_add_u64 v[0:1], v[128:129], 0, s[40:41]
	v_lshl_add_u64 v[0:1], v[0:1], 0, v[132:133]
	v_lshl_add_u64 v[2:3], v[0:1], 0, s[42:43]
	v_add_co_u32_e32 v0, vcc, 0x3000000, v0
	global_load_dwordx4 v[14:17], v[2:3], off offset:16
	s_nop 0
	v_addc_co_u32_e32 v1, vcc, 0, v1, vcc
	global_load_dwordx4 v[18:21], v[0:1], off offset:2560
	s_waitcnt vmcnt(0)
	v_and_b32_e32 v5, 0xffff0000, v14
	v_lshlrev_b32_e32 v4, 16, v14
	v_and_b32_e32 v7, 0xffff0000, v15
	v_lshlrev_b32_e32 v6, 16, v15
	v_and_b32_e32 v1, 0xffff0000, v16
	v_lshlrev_b32_e32 v0, 16, v16
	v_and_b32_e32 v3, 0xffff0000, v17
	v_and_b32_e32 v13, 0xffff0000, v18
	v_lshlrev_b32_e32 v12, 16, v18
	v_and_b32_e32 v15, 0xffff0000, v19
	v_lshlrev_b32_e32 v14, 16, v19
	v_and_b32_e32 v9, 0xffff0000, v20
	v_lshlrev_b32_e32 v8, 16, v20
	v_and_b32_e32 v11, 0xffff0000, v21
	v_lshlrev_b32_e32 v10, 16, v21
	v_lshlrev_b32_e32 v2, 16, v17
